# hand-written attention items; distribution v3
# speedup vs baseline: 1.0221x; 1.0221x over previous
.LBB0_227:
	v_readlane_b32 s100, v224, 34
	v_readlane_b32 s101, v224, 35
	s_waitcnt vmcnt(0) lgkmcnt(0)
	s_barrier
	s_load_dwordx4 s[52:55], s[100:101], 0x170
	s_load_dwordx4 s[56:59], s[100:101], 0x150
	v_readfirstlane_b32 s51, v131
	s_nop 0
	s_lshr_b32 s51, s51, 6
	s_and_b32 s2, s50, 1
	s_bfe_u32 s3, s50, 0x60001
	s_lshr_b32 s14, s50, 7
	s_lshl_b32 s15, s14, 11
	s_addk_i32 s15, 0x1000
	s_lshl_b32 s20, s3, 5
	s_add_i32 s20, s20, s15
	v_and_b32_e32 v0, 31, v131
	v_bfe_u32 v125, v131, 5, 1
	v_add_u32_e32 v124, s20, v0
	v_lshlrev_b32_e32 v124, 10, v124
	s_lshl_b32 s21, s2, 2
	s_add_i32 s21, s21, s51
	s_lshl_b32 s21, s21, 7
	v_lshl_add_u32 v124, v125, 4, v124
	v_add_u32_e32 v124, s21, v124
	s_load_dwordx2 s[20:21], s[100:101], 0x168
	s_waitcnt lgkmcnt(0)
	global_load_dwordx4 v[2:5], v124, s[20:21] offset:0
	global_load_dwordx4 v[6:9], v124, s[20:21] offset:32
	global_load_dwordx4 v[10:13], v124, s[20:21] offset:64
	global_load_dwordx4 v[14:17], v124, s[20:21] offset:96
	s_load_dwordx2 s[20:21], s[100:101], 0x68
	s_lshl_b32 vcc_lo, s2, 2
	s_add_i32 vcc_lo, vcc_lo, s51
	s_add_i32 vcc_lo, vcc_lo, s16
	s_lshl_b32 vcc_lo, vcc_lo, 2
	s_waitcnt lgkmcnt(0)
	s_add_u32 s20, s20, vcc_lo
	s_addc_u32 s21, s21, 0
	s_load_dword vcc_hi, s[20:21], 0x0
	s_lshl_b32 s51, s51, 10
	s_sub_u32 s20, s3, 4
	s_max_i32 s20, s20, 0
	s_add_i32 s21, s3, 5
	s_min_i32 s21, s21, 64
	s_sub_i32 s21, s21, s20
	s_waitcnt lgkmcnt(0)
	v_mov_b32_e32 v122, vcc_hi
	s_sub_i32 vcc_lo, s20, s3
	s_lshl_b32 vcc_lo, vcc_lo, 5
	s_addk_i32 vcc_lo, 0x80
	v_lshlrev_b32_e32 v127, 3, v125
	v_sub_u32_e32 v127, v127, v0
	v_add_u32_e32 v127, vcc_lo, v127
	s_mul_i32 vcc_lo, s2, 0x3000
	s_add_i32 vcc_lo, vcc_lo, s15
	s_lshl_b32 vcc_hi, s20, 5
	s_add_i32 vcc_lo, vcc_lo, vcc_hi
	s_lshl_b32 vcc_lo, vcc_lo, 7
	s_add_u32 s52, s52, vcc_lo
	s_addc_u32 s53, s53, 0
	s_lshl_b32 vcc_lo, s15, 8
	s_lshl_b32 vcc_hi, s2, 18
	s_add_i32 vcc_lo, vcc_lo, vcc_hi
	s_lshl_b32 vcc_hi, s20, 6
	s_add_i32 vcc_lo, vcc_lo, vcc_hi
	s_add_u32 s54, s54, vcc_lo
	s_addc_u32 s55, s55, 0
	s_lshl_b32 vcc_lo, s14, 2
	s_add_i32 vcc_lo, vcc_lo, s28
	s_lshl_b32 vcc_lo, vcc_lo, 1
	s_add_i32 vcc_lo, vcc_lo, s2
	s_lshl_b32 vcc_lo, vcc_lo, 16
	s_add_u32 s56, s56, vcc_lo
	s_addc_u32 s57, s57, 0
	s_add_u32 s58, s58, vcc_lo
	s_addc_u32 s59, s59, 0
	s_mov_b32 s2, s21
	s_mov_b32 s14, s21
	s_movk_i32 s3, 16
	s_add_i32 s15, s21, 16
	s_mov_b32 s21, s51
	s_mov_b32 s20, 0
	v_mul_f32_e32 v122, 0x3fb8aa3b, v122
	v_cvt_f32_u32_e32 v123, v125
	v_sub_f32_e32 v123, 1.0, v123
	v_mov_b32_e32 v18, 0
	v_mov_b32_e32 v34, 0
	v_mov_b32_e32 v19, 0
	v_mov_b32_e32 v35, 0
	v_mov_b32_e32 v20, 0
	v_mov_b32_e32 v36, 0
	v_mov_b32_e32 v21, 0
	v_mov_b32_e32 v37, 0
	v_mov_b32_e32 v22, 0
	v_mov_b32_e32 v38, 0
	v_mov_b32_e32 v23, 0
	v_mov_b32_e32 v39, 0
	v_mov_b32_e32 v24, 0
	v_mov_b32_e32 v40, 0
	v_mov_b32_e32 v25, 0
	v_mov_b32_e32 v41, 0
	v_mov_b32_e32 v26, 0
	v_mov_b32_e32 v42, 0
	v_mov_b32_e32 v27, 0
	v_mov_b32_e32 v43, 0
	v_mov_b32_e32 v28, 0
	v_mov_b32_e32 v44, 0
	v_mov_b32_e32 v29, 0
	v_mov_b32_e32 v45, 0
	v_mov_b32_e32 v30, 0
	v_mov_b32_e32 v46, 0
	v_mov_b32_e32 v31, 0
	v_mov_b32_e32 v47, 0
	v_mov_b32_e32 v32, 0
	v_mov_b32_e32 v48, 0
	v_mov_b32_e32 v33, 0
	v_mov_b32_e32 v49, 0
	v_lshrrev_b32_e32 v134, 4, v131
	v_xor_b32_e32 v134, v134, v131
	v_and_b32_e32 v118, 7, v134
	v_lshlrev_b32_e32 v118, 4, v118
	v_lshrrev_b32_e32 v124, 3, v131
	v_lshl_add_u32 v118, v124, 7, v118
	v_and_b32_e32 v134, 3, v134
	v_lshlrev_b32_e32 v134, 4, v134
	v_lshrrev_b32_e32 v124, 2, v131
	s_movk_i32 s51, 0x1000
	v_mad_u32_u24 v119, v124, s51, v134
	s_movk_i32 s51, 0x400
	v_mad_u32_u24 v120, v124, s51, v134
	v_mov_b32_e32 v121, v119
	v_and_b32_e32 v134, 0x13, v0
	v_bfe_u32 v124, v0, 2, 1
	v_lshl_or_b32 v134, v124, 3, v134
	v_bfe_u32 v124, v0, 3, 1
	v_lshl_or_b32 v134, v124, 2, v134
	v_bfe_u32 v124, v134, 1, 3
	v_xor_b32_e32 v124, v124, v125
	v_lshlrev_b32_e32 v134, 7, v134
	v_xor_b32_e32 v106, 0, v124
	v_lshl_or_b32 v106, v106, 4, v134
	v_xor_b32_e32 v107, 2, v124
	v_lshl_or_b32 v107, v107, 4, v134
	v_xor_b32_e32 v108, 4, v124
	v_lshl_or_b32 v108, v108, 4, v134
	v_xor_b32_e32 v109, 6, v124
	v_lshl_or_b32 v109, v109, 4, v134
	v_bfe_u32 v124, v0, 2, 2
	v_xor_b32_e32 v124, v124, v125
	v_lshlrev_b32_e32 v134, 6, v0
	v_add_u32_e32 v134, 0x1000, v134
	v_lshl_or_b32 v110, v124, 4, v134
	v_xor_b32_e32 v124, 2, v124
	v_lshl_or_b32 v111, v124, 4, v134
	s_mov_b32 m0, s21
	s_add_i32 s21, s21, 0x2000
	global_load_lds_dwordx4 v118, s[52:53]
	s_add_u32 m0, m0, 0x1000
	s_and_b32 s21, s21, 0xffff
	global_load_lds_dwordx4 v121, s[54:55]
	s_cmp_gt_u32 s2, 1
	s_cbranch_scc1 .Lat_la_a1_0
	s_cmp_eq_u32 s2, 1
	s_cbranch_scc1 .Lat_la_sw_0
	s_cmp_gt_u32 s3, 1
	s_cbranch_scc0 .Lat_la_dn_0
	s_sub_u32 s3, s3, 1
.Lat_la_ad_0:
	s_add_u32 s52, s52, 0x1000
	s_addc_u32 s53, s53, 0
	s_add_u32 s54, s54, 64
	s_addc_u32 s55, s55, 0
	s_branch .Lat_la_dn_0
.Lat_la_a1_0:
	s_sub_u32 s2, s2, 1
	s_branch .Lat_la_ad_0
.Lat_la_sw_0:
	s_mov_b32 s2, 0
	s_mov_b64 s[52:53], s[56:57]
	s_mov_b64 s[54:55], s[58:59]
	v_mov_b32_e32 v121, v120
.Lat_la_dn_0:
	s_mov_b32 m0, s21
	s_add_i32 s21, s21, 0x2000
	global_load_lds_dwordx4 v118, s[52:53]
	s_add_u32 m0, m0, 0x1000
	s_and_b32 s21, s21, 0xffff
	global_load_lds_dwordx4 v121, s[54:55]
	s_cmp_gt_u32 s2, 1
	s_cbranch_scc1 .Lat_la_a1_1
	s_cmp_eq_u32 s2, 1
	s_cbranch_scc1 .Lat_la_sw_1
	s_cmp_gt_u32 s3, 1
	s_cbranch_scc0 .Lat_la_dn_1
	s_sub_u32 s3, s3, 1

.Lat_la_dn_5:
.Lat_la_tile:
	s_waitcnt vmcnt(10)
	s_barrier
	v_add_u32_e32 v112, s20, v106
	v_add_u32_e32 v113, s20, v107
	v_add_u32_e32 v114, s20, v108
	v_add_u32_e32 v115, s20, v109
	v_add_u32_e32 v116, s20, v110
	v_add_u32_e32 v117, s20, v111
	ds_read_b128 v[66:69], v112
	ds_read_b128 v[70:73], v113
	ds_read_b128 v[74:77], v114
	ds_read_b128 v[78:81], v115
	ds_read_b128 v[82:85], v116
	ds_read_b128 v[86:89], v116 offset:2048
	ds_read_b128 v[90:93], v117
	ds_read_b128 v[94:97], v117 offset:2048
	s_add_i32 s20, s20, 0x2000
	s_and_b32 s20, s20, 0xffff
	s_mov_b32 m0, s21
	s_add_i32 s21, s21, 0x2000
	global_load_lds_dwordx4 v118, s[52:53]
	s_add_u32 m0, m0, 0x1000
	s_and_b32 s21, s21, 0xffff
	global_load_lds_dwordx4 v121, s[54:55]
	s_cmp_gt_u32 s2, 1
	s_cbranch_scc1 .Lat_la_a1_6
	s_cmp_eq_u32 s2, 1
	s_cbranch_scc1 .Lat_la_sw_6
	s_cmp_gt_u32 s3, 1
	s_cbranch_scc0 .Lat_la_dn_6
	s_sub_u32 s3, s3, 1

.Lat_la_dn_6:
	s_waitcnt lgkmcnt(7)
	v_mfma_f32_32x32x16_f16 v[50:65], v[66:69], v[2:5], 0
	s_waitcnt lgkmcnt(6)
	v_mfma_f32_32x32x16_f16 v[50:65], v[70:73], v[6:9], v[50:65]
	s_waitcnt lgkmcnt(5)
	v_mfma_f32_32x32x16_f16 v[50:65], v[74:77], v[10:13], v[50:65]
	s_waitcnt lgkmcnt(4)
	v_mfma_f32_32x32x16_f16 v[50:65], v[78:81], v[14:17], v[50:65]
	s_nop 15
	s_cmp_eq_u32 s14, 0
	s_cbranch_scc1 .Lat_la_nomask
	s_sub_u32 s14, s14, 1
	s_movk_i32 s51, 0x100
	v_add_u32_e32 v66, 0, v127
	v_add_u32_e32 v67, 1, v127
	v_cmp_lt_u32_e32 vcc, s51, v66
	v_add_u32_e32 v68, 2, v127
	v_cmp_lt_u32_e64 s[100:101], s51, v67
	v_cndmask_b32_e32 v50, v50, v166, vcc
	v_add_u32_e32 v69, 3, v127
	v_cmp_lt_u32_e32 vcc, s51, v68
	v_cndmask_b32_e64 v51, v51, v166, s[100:101]
	v_add_u32_e32 v70, 4, v127
	v_cmp_lt_u32_e64 s[100:101], s51, v69
	v_cndmask_b32_e32 v52, v52, v166, vcc
	v_add_u32_e32 v71, 5, v127
	v_cmp_lt_u32_e32 vcc, s51, v70
	v_cndmask_b32_e64 v53, v53, v166, s[100:101]
	v_add_u32_e32 v72, 6, v127
	v_cmp_lt_u32_e64 s[100:101], s51, v71
	v_cndmask_b32_e32 v54, v54, v166, vcc
	v_add_u32_e32 v73, 7, v127
	v_cmp_lt_u32_e32 vcc, s51, v72
	v_cndmask_b32_e64 v55, v55, v166, s[100:101]
	v_add_u32_e32 v74, 16, v127
	v_cmp_lt_u32_e64 s[100:101], s51, v73
	v_cndmask_b32_e32 v56, v56, v166, vcc
	v_add_u32_e32 v75, 17, v127
	v_cmp_lt_u32_e32 vcc, s51, v74
	v_cndmask_b32_e64 v57, v57, v166, s[100:101]
	v_add_u32_e32 v76, 18, v127
	v_cmp_lt_u32_e64 s[100:101], s51, v75
	v_cndmask_b32_e32 v58, v58, v166, vcc
	v_add_u32_e32 v77, 19, v127
	v_cmp_lt_u32_e32 vcc, s51, v76
	v_cndmask_b32_e64 v59, v59, v166, s[100:101]
	v_add_u32_e32 v78, 20, v127
	v_cmp_lt_u32_e64 s[100:101], s51, v77
	v_cndmask_b32_e32 v60, v60, v166, vcc
	v_add_u32_e32 v79, 21, v127
	v_cmp_lt_u32_e32 vcc, s51, v78
	v_cndmask_b32_e64 v61, v61, v166, s[100:101]
	v_add_u32_e32 v80, 22, v127
	v_cmp_lt_u32_e64 s[100:101], s51, v79
	v_cndmask_b32_e32 v62, v62, v166, vcc
	v_add_u32_e32 v81, 23, v127
	v_cmp_lt_u32_e32 vcc, s51, v80
	v_cndmask_b32_e64 v63, v63, v166, s[100:101]
	s_nop 0
	v_cmp_lt_u32_e64 s[100:101], s51, v81
	v_cndmask_b32_e32 v64, v64, v166, vcc
	s_nop 0
	s_nop 0
	v_cndmask_b32_e64 v65, v65, v166, s[100:101]
	v_add_u32_e32 v127, 32, v127
	v_max3_f32 v124, v50, v51, v52
	v_max3_f32 v124, v124, v53, v54
	v_max3_f32 v124, v124, v55, v56
	v_max3_f32 v124, v124, v57, v58
	v_max3_f32 v124, v124, v59, v60
	v_max3_f32 v124, v124, v61, v62
	v_max3_f32 v124, v124, v63, v64
	v_max_f32_e32 v124, v124, v65
	v_mov_b32_e32 v125, v124
	s_nop 1
	v_permlane32_swap_b32_e32 v125, v124
	v_max_f32_e32 v124, v124, v125
	v_mul_f32_e32 v124, 0x3fb8aa3b, v124
	v_max_f32_e32 v126, v122, v124
	v_sub_f32_e32 v128, v122, v126
	v_exp_f32_e32 v128, v128
	v_mov_b32_e32 v122, v126
	s_mov_b32 s51, 0x3fb8aa3b
	v_fma_f32 v50, v50, s51, -v126
	v_fma_f32 v51, v51, s51, -v126
	v_fma_f32 v52, v52, s51, -v126
	v_fma_f32 v53, v53, s51, -v126
	v_fma_f32 v54, v54, s51, -v126
	v_fma_f32 v55, v55, s51, -v126
	v_fma_f32 v56, v56, s51, -v126
	v_fma_f32 v57, v57, s51, -v126
	v_fma_f32 v58, v58, s51, -v126
	v_fma_f32 v59, v59, s51, -v126
	v_fma_f32 v60, v60, s51, -v126
	v_fma_f32 v61, v61, s51, -v126
	v_fma_f32 v62, v62, s51, -v126
	v_fma_f32 v63, v63, s51, -v126
	v_fma_f32 v64, v64, s51, -v126
	v_fma_f32 v65, v65, s51, -v126
	v_exp_f32_e32 v50, v50
	v_exp_f32_e32 v51, v51
	v_exp_f32_e32 v52, v52
	v_exp_f32_e32 v53, v53
	v_exp_f32_e32 v54, v54
	v_exp_f32_e32 v55, v55
	v_exp_f32_e32 v56, v56
	v_exp_f32_e32 v57, v57
	v_exp_f32_e32 v58, v58
	v_exp_f32_e32 v59, v59
	v_exp_f32_e32 v60, v60
	v_exp_f32_e32 v61, v61
	v_exp_f32_e32 v62, v62
	v_exp_f32_e32 v63, v63
	v_exp_f32_e32 v64, v64
	v_exp_f32_e32 v65, v65
	s_nop 0
	v_pk_add_f32 v[66:67], v[50:51], v[52:53]
	v_pk_add_f32 v[68:69], v[54:55], v[56:57]
	v_pk_add_f32 v[70:71], v[58:59], v[60:61]
	v_pk_add_f32 v[72:73], v[62:63], v[64:65]
	v_pk_add_f32 v[66:67], v[66:67], v[68:69]
	v_pk_add_f32 v[70:71], v[70:71], v[72:73]
	v_pk_add_f32 v[66:67], v[66:67], v[70:71]
	v_add_f32_e32 v66, v66, v67
	v_fma_f32 v123, v123, v128, v66
	v_pk_mul_f32 v[18:19], v[18:19], v[128:129] op_sel_hi:[1,0]
	v_pk_mul_f32 v[34:35], v[34:35], v[128:129] op_sel_hi:[1,0]
	v_pk_mul_f32 v[20:21], v[20:21], v[128:129] op_sel_hi:[1,0]
	v_pk_mul_f32 v[36:37], v[36:37], v[128:129] op_sel_hi:[1,0]
	v_pk_mul_f32 v[22:23], v[22:23], v[128:129] op_sel_hi:[1,0]
	v_pk_mul_f32 v[38:39], v[38:39], v[128:129] op_sel_hi:[1,0]
	v_pk_mul_f32 v[24:25], v[24:25], v[128:129] op_sel_hi:[1,0]
	v_pk_mul_f32 v[40:41], v[40:41], v[128:129] op_sel_hi:[1,0]
	v_pk_mul_f32 v[26:27], v[26:27], v[128:129] op_sel_hi:[1,0]
	v_pk_mul_f32 v[42:43], v[42:43], v[128:129] op_sel_hi:[1,0]
	v_pk_mul_f32 v[28:29], v[28:29], v[128:129] op_sel_hi:[1,0]
	v_pk_mul_f32 v[44:45], v[44:45], v[128:129] op_sel_hi:[1,0]
	v_pk_mul_f32 v[30:31], v[30:31], v[128:129] op_sel_hi:[1,0]
	v_pk_mul_f32 v[46:47], v[46:47], v[128:129] op_sel_hi:[1,0]
	v_pk_mul_f32 v[32:33], v[32:33], v[128:129] op_sel_hi:[1,0]
	v_pk_mul_f32 v[48:49], v[48:49], v[128:129] op_sel_hi:[1,0]
	v_cvt_pk_f16_f32 v98, v50, v51
	v_cvt_pk_f16_f32 v99, v52, v53
	v_cvt_pk_f16_f32 v100, v54, v55
	v_cvt_pk_f16_f32 v101, v56, v57
	v_cvt_pk_f16_f32 v102, v58, v59
	v_cvt_pk_f16_f32 v103, v60, v61
	v_cvt_pk_f16_f32 v104, v62, v63
	v_cvt_pk_f16_f32 v105, v64, v65
	s_waitcnt lgkmcnt(0)
	s_nop 1
	v_mfma_f32_32x32x16_f16 v[18:33], v[82:85], v[98:101], v[18:33]
	v_mfma_f32_32x32x16_f16 v[34:49], v[86:89], v[98:101], v[34:49]
	v_mfma_f32_32x32x16_f16 v[18:33], v[90:93], v[102:105], v[18:33]
	v_mfma_f32_32x32x16_f16 v[34:49], v[94:97], v[102:105], v[34:49]
	s_branch .Lat_la_next
.Lat_la_nomask:
	v_max3_f32 v124, v50, v51, v52
	v_max3_f32 v124, v124, v53, v54
	v_max3_f32 v124, v124, v55, v56
	v_max3_f32 v124, v124, v57, v58
	v_max3_f32 v124, v124, v59, v60
	v_max3_f32 v124, v124, v61, v62
	v_max3_f32 v124, v124, v63, v64
	v_max_f32_e32 v124, v124, v65
	v_mov_b32_e32 v125, v124
	s_nop 1
	v_permlane32_swap_b32_e32 v125, v124
	v_max_f32_e32 v124, v124, v125
	v_mul_f32_e32 v124, 0x3fb8aa3b, v124
	v_max_f32_e32 v126, v122, v124
	v_sub_f32_e32 v128, v122, v126
	v_exp_f32_e32 v128, v128
	v_mov_b32_e32 v122, v126
	s_mov_b32 s51, 0x3fb8aa3b
	v_fma_f32 v50, v50, s51, -v126
	v_fma_f32 v51, v51, s51, -v126
	v_fma_f32 v52, v52, s51, -v126
	v_fma_f32 v53, v53, s51, -v126
	v_fma_f32 v54, v54, s51, -v126
	v_fma_f32 v55, v55, s51, -v126
	v_fma_f32 v56, v56, s51, -v126
	v_fma_f32 v57, v57, s51, -v126
	v_fma_f32 v58, v58, s51, -v126
	v_fma_f32 v59, v59, s51, -v126
	v_fma_f32 v60, v60, s51, -v126
	v_fma_f32 v61, v61, s51, -v126
	v_fma_f32 v62, v62, s51, -v126
	v_fma_f32 v63, v63, s51, -v126
	v_fma_f32 v64, v64, s51, -v126
	v_fma_f32 v65, v65, s51, -v126
	v_exp_f32_e32 v50, v50
	v_exp_f32_e32 v51, v51
	v_exp_f32_e32 v52, v52
	v_exp_f32_e32 v53, v53
	v_exp_f32_e32 v54, v54
	v_exp_f32_e32 v55, v55
	v_exp_f32_e32 v56, v56
	v_exp_f32_e32 v57, v57
	v_exp_f32_e32 v58, v58
	v_exp_f32_e32 v59, v59
	v_exp_f32_e32 v60, v60
	v_exp_f32_e32 v61, v61
	v_exp_f32_e32 v62, v62
	v_exp_f32_e32 v63, v63
	v_exp_f32_e32 v64, v64
	v_exp_f32_e32 v65, v65
	s_nop 0
	v_pk_add_f32 v[66:67], v[50:51], v[52:53]
	v_pk_add_f32 v[68:69], v[54:55], v[56:57]
	v_pk_add_f32 v[70:71], v[58:59], v[60:61]
	v_pk_add_f32 v[72:73], v[62:63], v[64:65]
	v_pk_add_f32 v[66:67], v[66:67], v[68:69]
	v_pk_add_f32 v[70:71], v[70:71], v[72:73]
	v_pk_add_f32 v[66:67], v[66:67], v[70:71]
	v_add_f32_e32 v66, v66, v67
	v_fma_f32 v123, v123, v128, v66
	v_pk_mul_f32 v[18:19], v[18:19], v[128:129] op_sel_hi:[1,0]
	v_pk_mul_f32 v[34:35], v[34:35], v[128:129] op_sel_hi:[1,0]
	v_pk_mul_f32 v[20:21], v[20:21], v[128:129] op_sel_hi:[1,0]
	v_pk_mul_f32 v[36:37], v[36:37], v[128:129] op_sel_hi:[1,0]
	v_pk_mul_f32 v[22:23], v[22:23], v[128:129] op_sel_hi:[1,0]
	v_pk_mul_f32 v[38:39], v[38:39], v[128:129] op_sel_hi:[1,0]
	v_pk_mul_f32 v[24:25], v[24:25], v[128:129] op_sel_hi:[1,0]
	v_pk_mul_f32 v[40:41], v[40:41], v[128:129] op_sel_hi:[1,0]
	v_pk_mul_f32 v[26:27], v[26:27], v[128:129] op_sel_hi:[1,0]
	v_pk_mul_f32 v[42:43], v[42:43], v[128:129] op_sel_hi:[1,0]
	v_pk_mul_f32 v[28:29], v[28:29], v[128:129] op_sel_hi:[1,0]
	v_pk_mul_f32 v[44:45], v[44:45], v[128:129] op_sel_hi:[1,0]
	v_pk_mul_f32 v[30:31], v[30:31], v[128:129] op_sel_hi:[1,0]
	v_pk_mul_f32 v[46:47], v[46:47], v[128:129] op_sel_hi:[1,0]
	v_pk_mul_f32 v[32:33], v[32:33], v[128:129] op_sel_hi:[1,0]
	v_pk_mul_f32 v[48:49], v[48:49], v[128:129] op_sel_hi:[1,0]
	v_cvt_pk_f16_f32 v98, v50, v51
	v_cvt_pk_f16_f32 v99, v52, v53
	v_cvt_pk_f16_f32 v100, v54, v55
	v_cvt_pk_f16_f32 v101, v56, v57
	v_cvt_pk_f16_f32 v102, v58, v59
	v_cvt_pk_f16_f32 v103, v60, v61
	v_cvt_pk_f16_f32 v104, v62, v63
	v_cvt_pk_f16_f32 v105, v64, v65
	s_waitcnt lgkmcnt(0)
	s_nop 1
	v_mfma_f32_32x32x16_f16 v[18:33], v[82:85], v[98:101], v[18:33]
	v_mfma_f32_32x32x16_f16 v[34:49], v[86:89], v[98:101], v[34:49]
	v_mfma_f32_32x32x16_f16 v[18:33], v[90:93], v[102:105], v[18:33]
	v_mfma_f32_32x32x16_f16 v[34:49], v[94:97], v[102:105], v[34:49]
.Lat_la_next:
	s_sub_u32 s15, s15, 1
	s_cmp_lg_u32 s15, 0
	s_cbranch_scc1 .Lat_la_tile
	v_readlane_b32 s100, v224, 34
	v_readlane_b32 s101, v224, 35
	v_mov_b32_e32 v125, v123
	s_load_dwordx2 s[20:21], s[100:101], 0x160
	s_nop 0
	v_permlane32_swap_b32_e32 v125, v123
	v_add_f32_e32 v123, v123, v125
	v_rcp_f32_e32 v128, v123
	v_readfirstlane_b32 s51, v131
	s_and_b32 s2, s50, 1
	s_lshr_b32 s51, s51, 6
	s_lshl_b32 s2, s2, 2
	s_add_i32 s2, s2, s51
	s_lshl_b32 s2, s2, 7
	s_bfe_u32 s3, s50, 0x60001
	s_lshr_b32 s14, s50, 7
	s_lshl_b32 s14, s14, 11
	s_addk_i32 s14, 0x1000
	s_lshl_b32 s3, s3, 5
	s_add_i32 s3, s3, s14
	v_and_b32_e32 v0, 31, v131
	v_add_u32_e32 v0, s3, v0
	v_lshlrev_b32_e32 v0, 11, v0
	v_bfe_u32 v134, v131, 5, 1
	v_lshl_add_u32 v0, v134, 3, v0
	v_add_u32_e32 v0, s2, v0
	s_nop 8
	v_pk_mul_f32 v[18:19], v[18:19], v[128:129] op_sel_hi:[1,0]
	v_pk_mul_f32 v[34:35], v[34:35], v[128:129] op_sel_hi:[1,0]
	v_pk_mul_f32 v[20:21], v[20:21], v[128:129] op_sel_hi:[1,0]
	v_pk_mul_f32 v[36:37], v[36:37], v[128:129] op_sel_hi:[1,0]
	v_pk_mul_f32 v[22:23], v[22:23], v[128:129] op_sel_hi:[1,0]
	v_pk_mul_f32 v[38:39], v[38:39], v[128:129] op_sel_hi:[1,0]
	v_pk_mul_f32 v[24:25], v[24:25], v[128:129] op_sel_hi:[1,0]
	v_pk_mul_f32 v[40:41], v[40:41], v[128:129] op_sel_hi:[1,0]
	v_pk_mul_f32 v[26:27], v[26:27], v[128:129] op_sel_hi:[1,0]
	v_pk_mul_f32 v[42:43], v[42:43], v[128:129] op_sel_hi:[1,0]
	v_pk_mul_f32 v[28:29], v[28:29], v[128:129] op_sel_hi:[1,0]
	v_pk_mul_f32 v[44:45], v[44:45], v[128:129] op_sel_hi:[1,0]
	v_pk_mul_f32 v[30:31], v[30:31], v[128:129] op_sel_hi:[1,0]
	v_pk_mul_f32 v[46:47], v[46:47], v[128:129] op_sel_hi:[1,0]
	v_pk_mul_f32 v[32:33], v[32:33], v[128:129] op_sel_hi:[1,0]
	v_pk_mul_f32 v[48:49], v[48:49], v[128:129] op_sel_hi:[1,0]
	v_cvt_pk_f16_f32 v50, v18, v19
	v_cvt_pk_f16_f32 v58, v34, v35
	v_cvt_pk_f16_f32 v51, v20, v21
	v_cvt_pk_f16_f32 v59, v36, v37
	v_cvt_pk_f16_f32 v52, v22, v23
	v_cvt_pk_f16_f32 v60, v38, v39
	v_cvt_pk_f16_f32 v53, v24, v25
	v_cvt_pk_f16_f32 v61, v40, v41
	v_cvt_pk_f16_f32 v54, v26, v27
	v_cvt_pk_f16_f32 v62, v42, v43
	v_cvt_pk_f16_f32 v55, v28, v29
	v_cvt_pk_f16_f32 v63, v44, v45
	v_cvt_pk_f16_f32 v56, v30, v31
	v_cvt_pk_f16_f32 v64, v46, v47
	v_cvt_pk_f16_f32 v57, v32, v33
	v_cvt_pk_f16_f32 v65, v48, v49
	s_waitcnt lgkmcnt(0)
	global_store_dwordx2 v0, v[50:51], s[20:21] offset:0
	global_store_dwordx2 v0, v[58:59], s[20:21] offset:64
	global_store_dwordx2 v0, v[52:53], s[20:21] offset:16
	global_store_dwordx2 v0, v[60:61], s[20:21] offset:80
	global_store_dwordx2 v0, v[54:55], s[20:21] offset:32
	global_store_dwordx2 v0, v[62:63], s[20:21] offset:96
	global_store_dwordx2 v0, v[56:57], s[20:21] offset:48
	global_store_dwordx2 v0, v[64:65], s[20:21] offset:112
	s_waitcnt vmcnt(0)
	s_add_i32 s50, s50, s4
	s_cmpk_gt_i32 s50, 0x1ff
	s_cbranch_scc0 .LBB0_227

.LBB0_250:
	v_readlane_b32 s100, v224, 34
	v_readlane_b32 s101, v224, 35
	s_waitcnt vmcnt(0) lgkmcnt(0)
	s_barrier
	s_load_dwordx4 s[52:55], s[100:101], 0x170
	s_load_dwordx4 s[64:67], s[100:101], 0x150
	v_readfirstlane_b32 s59, v131
	s_nop 0
	s_lshr_b32 s59, s59, 6
	s_and_b32 s2, s58, 1
	s_bfe_u32 s3, s58, 0x30001
	s_lshr_b32 s14, s58, 4
	s_lshl_b32 s15, s14, 8
	s_lshl_b32 s20, s3, 5
	s_add_i32 s20, s20, s15
	v_and_b32_e32 v0, 31, v131
	v_bfe_u32 v125, v131, 5, 1
	v_add_u32_e32 v124, s20, v0
	v_lshlrev_b32_e32 v124, 10, v124
	s_lshl_b32 s21, s2, 2
	s_add_i32 s21, s21, s59
	s_lshl_b32 s21, s21, 7
	v_lshl_add_u32 v124, v125, 4, v124
	v_add_u32_e32 v124, s21, v124
	s_load_dwordx2 s[20:21], s[100:101], 0x168
	s_waitcnt lgkmcnt(0)
	global_load_dwordx4 v[2:5], v124, s[20:21] offset:0
	global_load_dwordx4 v[6:9], v124, s[20:21] offset:32
	global_load_dwordx4 v[10:13], v124, s[20:21] offset:64
	global_load_dwordx4 v[14:17], v124, s[20:21] offset:96
	s_load_dwordx2 s[20:21], s[100:101], 0x68
	s_lshl_b32 vcc_lo, s2, 2
	s_add_i32 vcc_lo, vcc_lo, s59
	s_add_i32 vcc_lo, vcc_lo, s16
	s_lshl_b32 vcc_lo, vcc_lo, 2
	s_waitcnt lgkmcnt(0)
	s_add_u32 s20, s20, vcc_lo
	s_addc_u32 s21, s21, 0
	s_load_dword vcc_hi, s[20:21], 0x0
	s_lshl_b32 s59, s59, 10
	s_waitcnt lgkmcnt(0)
	v_mov_b32_e32 v122, vcc_hi
	s_mul_i32 vcc_lo, s2, 0x3000
	s_add_i32 vcc_lo, vcc_lo, s15
	s_lshl_b32 vcc_lo, vcc_lo, 7
	s_add_u32 s52, s52, vcc_lo
	s_addc_u32 s53, s53, 0
	s_lshl_b32 vcc_lo, s15, 8
	s_lshl_b32 vcc_hi, s2, 15
	s_add_i32 vcc_lo, vcc_lo, vcc_hi
	s_add_u32 s54, s54, vcc_lo
	s_addc_u32 s55, s55, 0
	s_mov_b32 s2, 0
	s_mov_b32 s14, 0
	s_movk_i32 s3, 8
	s_movk_i32 s15, 8
	s_mov_b64 s[64:65], s[52:53]
	s_mov_b64 s[66:67], s[54:55]
	s_mov_b32 s21, s59
	s_mov_b32 s20, 0
	v_mul_f32_e32 v122, 0x3fb8aa3b, v122
	v_cvt_f32_u32_e32 v123, v125
	v_sub_f32_e32 v123, 1.0, v123
	v_mov_b32_e32 v18, 0
	v_mov_b32_e32 v34, 0
	v_mov_b32_e32 v19, 0
	v_mov_b32_e32 v35, 0
	v_mov_b32_e32 v20, 0
	v_mov_b32_e32 v36, 0
	v_mov_b32_e32 v21, 0
	v_mov_b32_e32 v37, 0
	v_mov_b32_e32 v22, 0
	v_mov_b32_e32 v38, 0
	v_mov_b32_e32 v23, 0
	v_mov_b32_e32 v39, 0
	v_mov_b32_e32 v24, 0
	v_mov_b32_e32 v40, 0
	v_mov_b32_e32 v25, 0
	v_mov_b32_e32 v41, 0
	v_mov_b32_e32 v26, 0
	v_mov_b32_e32 v42, 0
	v_mov_b32_e32 v27, 0
	v_mov_b32_e32 v43, 0
	v_mov_b32_e32 v28, 0
	v_mov_b32_e32 v44, 0
	v_mov_b32_e32 v29, 0
	v_mov_b32_e32 v45, 0
	v_mov_b32_e32 v30, 0
	v_mov_b32_e32 v46, 0
	v_mov_b32_e32 v31, 0
	v_mov_b32_e32 v47, 0
	v_mov_b32_e32 v32, 0
	v_mov_b32_e32 v48, 0
	v_mov_b32_e32 v33, 0
	v_mov_b32_e32 v49, 0
	v_lshrrev_b32_e32 v134, 4, v131
	v_xor_b32_e32 v134, v134, v131
	v_and_b32_e32 v118, 7, v134
	v_lshlrev_b32_e32 v118, 4, v118
	v_lshrrev_b32_e32 v124, 3, v131
	v_lshl_add_u32 v118, v124, 7, v118
	v_and_b32_e32 v134, 3, v134
	v_lshlrev_b32_e32 v134, 4, v134
	v_lshrrev_b32_e32 v124, 2, v131
	s_movk_i32 s59, 0x200
	v_mad_u32_u24 v119, v124, s59, v134
	s_movk_i32 s59, 0x200
	v_mad_u32_u24 v120, v124, s59, v134
	v_mov_b32_e32 v121, v120
	v_and_b32_e32 v134, 0x13, v0
	v_bfe_u32 v124, v0, 2, 1
	v_lshl_or_b32 v134, v124, 3, v134
	v_bfe_u32 v124, v0, 3, 1
	v_lshl_or_b32 v134, v124, 2, v134
	v_bfe_u32 v124, v134, 1, 3
	v_xor_b32_e32 v124, v124, v125
	v_lshlrev_b32_e32 v134, 7, v134
	v_xor_b32_e32 v106, 0, v124
	v_lshl_or_b32 v106, v106, 4, v134
	v_xor_b32_e32 v107, 2, v124
	v_lshl_or_b32 v107, v107, 4, v134
	v_xor_b32_e32 v108, 4, v124
	v_lshl_or_b32 v108, v108, 4, v134
	v_xor_b32_e32 v109, 6, v124
	v_lshl_or_b32 v109, v109, 4, v134
	v_bfe_u32 v124, v0, 2, 2
	v_xor_b32_e32 v124, v124, v125
	v_lshlrev_b32_e32 v134, 6, v0
	v_add_u32_e32 v134, 0x1000, v134
	v_lshl_or_b32 v110, v124, 4, v134
	v_xor_b32_e32 v124, 2, v124
	v_lshl_or_b32 v111, v124, 4, v134
	s_mov_b32 m0, s21
	s_add_i32 s21, s21, 0x2000
	global_load_lds_dwordx4 v118, s[52:53]
	s_add_u32 m0, m0, 0x1000
	s_and_b32 s21, s21, 0xffff
	global_load_lds_dwordx4 v121, s[54:55]
	s_cmp_gt_u32 s2, 1
	s_cbranch_scc1 .Lat_ca_a1_0
	s_cmp_eq_u32 s2, 1
	s_cbranch_scc1 .Lat_ca_sw_0
	s_cmp_gt_u32 s3, 1
	s_cbranch_scc0 .Lat_ca_dn_0
	s_sub_u32 s3, s3, 1

.Lat_ca_sw_0:
	s_mov_b32 s2, 0
	s_mov_b64 s[52:53], s[64:65]
	s_mov_b64 s[54:55], s[66:67]
	v_mov_b32_e32 v121, v120

.Lat_ca_dn_6:
	s_waitcnt lgkmcnt(7)
	v_mfma_f32_32x32x16_f16 v[50:65], v[66:69], v[2:5], 0
	s_waitcnt lgkmcnt(6)
	v_mfma_f32_32x32x16_f16 v[50:65], v[70:73], v[6:9], v[50:65]
	s_waitcnt lgkmcnt(5)
	v_mfma_f32_32x32x16_f16 v[50:65], v[74:77], v[10:13], v[50:65]
	s_waitcnt lgkmcnt(4)
	v_mfma_f32_32x32x16_f16 v[50:65], v[78:81], v[14:17], v[50:65]
	s_nop 15
	v_max3_f32 v124, v50, v51, v52
	v_max3_f32 v124, v124, v53, v54
	v_max3_f32 v124, v124, v55, v56
	v_max3_f32 v124, v124, v57, v58
	v_max3_f32 v124, v124, v59, v60
	v_max3_f32 v124, v124, v61, v62
	v_max3_f32 v124, v124, v63, v64
	v_max_f32_e32 v124, v124, v65
	v_mov_b32_e32 v125, v124
	s_nop 1
	v_permlane32_swap_b32_e32 v125, v124
	v_max_f32_e32 v124, v124, v125
	v_mul_f32_e32 v124, 0x3fb8aa3b, v124
	v_max_f32_e32 v126, v122, v124
	v_sub_f32_e32 v128, v122, v126
	v_exp_f32_e32 v128, v128
	v_mov_b32_e32 v122, v126
	s_mov_b32 s59, 0x3fb8aa3b
	v_fma_f32 v50, v50, s59, -v126
	v_fma_f32 v51, v51, s59, -v126
	v_fma_f32 v52, v52, s59, -v126
	v_fma_f32 v53, v53, s59, -v126
	v_fma_f32 v54, v54, s59, -v126
	v_fma_f32 v55, v55, s59, -v126
	v_fma_f32 v56, v56, s59, -v126
	v_fma_f32 v57, v57, s59, -v126
	v_fma_f32 v58, v58, s59, -v126
	v_fma_f32 v59, v59, s59, -v126
	v_fma_f32 v60, v60, s59, -v126
	v_fma_f32 v61, v61, s59, -v126
	v_fma_f32 v62, v62, s59, -v126
	v_fma_f32 v63, v63, s59, -v126
	v_fma_f32 v64, v64, s59, -v126
	v_fma_f32 v65, v65, s59, -v126
	v_exp_f32_e32 v50, v50
	v_exp_f32_e32 v51, v51
	v_exp_f32_e32 v52, v52
	v_exp_f32_e32 v53, v53
	v_exp_f32_e32 v54, v54
	v_exp_f32_e32 v55, v55
	v_exp_f32_e32 v56, v56
	v_exp_f32_e32 v57, v57
	v_exp_f32_e32 v58, v58
	v_exp_f32_e32 v59, v59
	v_exp_f32_e32 v60, v60
	v_exp_f32_e32 v61, v61
	v_exp_f32_e32 v62, v62
	v_exp_f32_e32 v63, v63
	v_exp_f32_e32 v64, v64
	v_exp_f32_e32 v65, v65
	s_nop 0
	v_pk_add_f32 v[66:67], v[50:51], v[52:53]
	v_pk_add_f32 v[68:69], v[54:55], v[56:57]
	v_pk_add_f32 v[70:71], v[58:59], v[60:61]
	v_pk_add_f32 v[72:73], v[62:63], v[64:65]
	v_pk_add_f32 v[66:67], v[66:67], v[68:69]
	v_pk_add_f32 v[70:71], v[70:71], v[72:73]
	v_pk_add_f32 v[66:67], v[66:67], v[70:71]
	v_add_f32_e32 v66, v66, v67
	v_fma_f32 v123, v123, v128, v66
	v_pk_mul_f32 v[18:19], v[18:19], v[128:129] op_sel_hi:[1,0]
	v_pk_mul_f32 v[34:35], v[34:35], v[128:129] op_sel_hi:[1,0]
	v_pk_mul_f32 v[20:21], v[20:21], v[128:129] op_sel_hi:[1,0]
	v_pk_mul_f32 v[36:37], v[36:37], v[128:129] op_sel_hi:[1,0]
	v_pk_mul_f32 v[22:23], v[22:23], v[128:129] op_sel_hi:[1,0]
	v_pk_mul_f32 v[38:39], v[38:39], v[128:129] op_sel_hi:[1,0]
	v_pk_mul_f32 v[24:25], v[24:25], v[128:129] op_sel_hi:[1,0]
	v_pk_mul_f32 v[40:41], v[40:41], v[128:129] op_sel_hi:[1,0]
	v_pk_mul_f32 v[26:27], v[26:27], v[128:129] op_sel_hi:[1,0]
	v_pk_mul_f32 v[42:43], v[42:43], v[128:129] op_sel_hi:[1,0]
	v_pk_mul_f32 v[28:29], v[28:29], v[128:129] op_sel_hi:[1,0]
	v_pk_mul_f32 v[44:45], v[44:45], v[128:129] op_sel_hi:[1,0]
	v_pk_mul_f32 v[30:31], v[30:31], v[128:129] op_sel_hi:[1,0]
	v_pk_mul_f32 v[46:47], v[46:47], v[128:129] op_sel_hi:[1,0]
	v_pk_mul_f32 v[32:33], v[32:33], v[128:129] op_sel_hi:[1,0]
	v_pk_mul_f32 v[48:49], v[48:49], v[128:129] op_sel_hi:[1,0]
	v_cvt_pk_f16_f32 v98, v50, v51
	v_cvt_pk_f16_f32 v99, v52, v53
	v_cvt_pk_f16_f32 v100, v54, v55
	v_cvt_pk_f16_f32 v101, v56, v57
	v_cvt_pk_f16_f32 v102, v58, v59
	v_cvt_pk_f16_f32 v103, v60, v61
	v_cvt_pk_f16_f32 v104, v62, v63
	v_cvt_pk_f16_f32 v105, v64, v65
	s_waitcnt lgkmcnt(0)
	s_nop 1
	v_mfma_f32_32x32x16_f16 v[18:33], v[82:85], v[98:101], v[18:33]
	v_mfma_f32_32x32x16_f16 v[34:49], v[86:89], v[98:101], v[34:49]
	v_mfma_f32_32x32x16_f16 v[18:33], v[90:93], v[102:105], v[18:33]
	v_mfma_f32_32x32x16_f16 v[34:49], v[94:97], v[102:105], v[34:49]
.Lat_ca_next:
	s_sub_u32 s15, s15, 1
	s_cmp_lg_u32 s15, 0
	s_cbranch_scc1 .Lat_ca_tile
	v_readlane_b32 s100, v224, 34
	v_readlane_b32 s101, v224, 35
	v_mov_b32_e32 v125, v123
	s_load_dwordx2 s[20:21], s[100:101], 0x160
	s_nop 0
	v_permlane32_swap_b32_e32 v125, v123
	v_add_f32_e32 v123, v123, v125
	v_rcp_f32_e32 v128, v123
	v_readfirstlane_b32 s59, v131
	s_and_b32 s2, s58, 1
	s_lshr_b32 s59, s59, 6
	s_lshl_b32 s2, s2, 2
	s_add_i32 s2, s2, s59
	s_lshl_b32 s2, s2, 7
	s_bfe_u32 s3, s58, 0x30001
	s_lshr_b32 s14, s58, 4
	s_lshl_b32 s14, s14, 8
	s_lshl_b32 s3, s3, 5
	s_add_i32 s3, s3, s14
	v_and_b32_e32 v0, 31, v131
	v_add_u32_e32 v0, s3, v0
	v_lshlrev_b32_e32 v0, 11, v0
	v_bfe_u32 v134, v131, 5, 1
	v_lshl_add_u32 v0, v134, 3, v0
	v_add_u32_e32 v0, s2, v0
	s_nop 8
	v_pk_mul_f32 v[18:19], v[18:19], v[128:129] op_sel_hi:[1,0]
	v_pk_mul_f32 v[34:35], v[34:35], v[128:129] op_sel_hi:[1,0]
	v_pk_mul_f32 v[20:21], v[20:21], v[128:129] op_sel_hi:[1,0]
	v_pk_mul_f32 v[36:37], v[36:37], v[128:129] op_sel_hi:[1,0]
	v_pk_mul_f32 v[22:23], v[22:23], v[128:129] op_sel_hi:[1,0]
	v_pk_mul_f32 v[38:39], v[38:39], v[128:129] op_sel_hi:[1,0]
	v_pk_mul_f32 v[24:25], v[24:25], v[128:129] op_sel_hi:[1,0]
	v_pk_mul_f32 v[40:41], v[40:41], v[128:129] op_sel_hi:[1,0]
	v_pk_mul_f32 v[26:27], v[26:27], v[128:129] op_sel_hi:[1,0]
	v_pk_mul_f32 v[42:43], v[42:43], v[128:129] op_sel_hi:[1,0]
	v_pk_mul_f32 v[28:29], v[28:29], v[128:129] op_sel_hi:[1,0]
	v_pk_mul_f32 v[44:45], v[44:45], v[128:129] op_sel_hi:[1,0]
	v_pk_mul_f32 v[30:31], v[30:31], v[128:129] op_sel_hi:[1,0]
	v_pk_mul_f32 v[46:47], v[46:47], v[128:129] op_sel_hi:[1,0]
	v_pk_mul_f32 v[32:33], v[32:33], v[128:129] op_sel_hi:[1,0]
	v_pk_mul_f32 v[48:49], v[48:49], v[128:129] op_sel_hi:[1,0]
	v_cvt_pk_f16_f32 v50, v18, v19
	v_cvt_pk_f16_f32 v58, v34, v35
	v_cvt_pk_f16_f32 v51, v20, v21
	v_cvt_pk_f16_f32 v59, v36, v37
	v_cvt_pk_f16_f32 v52, v22, v23
	v_cvt_pk_f16_f32 v60, v38, v39
	v_cvt_pk_f16_f32 v53, v24, v25
	v_cvt_pk_f16_f32 v61, v40, v41
	v_cvt_pk_f16_f32 v54, v26, v27
	v_cvt_pk_f16_f32 v62, v42, v43
	v_cvt_pk_f16_f32 v55, v28, v29
	v_cvt_pk_f16_f32 v63, v44, v45
	v_cvt_pk_f16_f32 v56, v30, v31
	v_cvt_pk_f16_f32 v64, v46, v47
	v_cvt_pk_f16_f32 v57, v32, v33
	v_cvt_pk_f16_f32 v65, v48, v49
	s_waitcnt lgkmcnt(0)
	global_store_dwordx2 v0, v[50:51], s[20:21] offset:0
	global_store_dwordx2 v0, v[58:59], s[20:21] offset:64
	global_store_dwordx2 v0, v[52:53], s[20:21] offset:16
	global_store_dwordx2 v0, v[60:61], s[20:21] offset:80
	global_store_dwordx2 v0, v[54:55], s[20:21] offset:32
	global_store_dwordx2 v0, v[62:63], s[20:21] offset:96
	global_store_dwordx2 v0, v[56:57], s[20:21] offset:48
	global_store_dwordx2 v0, v[64:65], s[20:21] offset:112
	s_waitcnt vmcnt(0)
	v_readlane_b32 s4, v224, 20
	s_nop 0
	s_add_i32 s58, s58, s4
	s_cmpk_gt_i32 s58, 0xff
	s_cbranch_scc0 .LBB0_250
	v_readlane_b32 s54, v224, 28
	v_readlane_b32 s55, v224, 29
	v_readlane_b32 s91, v224, 23
